# P4 work placement: XCD-local work index remapped j -> ((j&31)<<1)|(j>>5) so workgroups ranked j and j+32 take tiles of the same weight column block (placement only; inverse applied at phase exit)
# baseline (speedup 1.0000x reference)
.LBB0_685:
	s_cmp_lg_u32 s40, 0
	s_cbranch_scc1 .Lnsj_old
	s_or_b32 s41, 1, s55
	s_cmp_gt_i32 s41, s44
	s_cbranch_scc1 .Lnsj_old
	v_add_u32_e32 v0, s53, v141
	v_add_u32_e32 v66, v0, v166
	ds_read_b128 v[66:69], v66 offset:34816
	v_add_u32_e32 v98, v0, v172
	ds_read_b128 v[98:101], v98 offset:34816
	v_add_u32_e32 v102, v0, v173
	ds_read_b128 v[102:105], v102 offset:34816
	v_add_u32_e32 v178, v0, v174
	ds_read_b128 v[178:181], v178 offset:34816
	v_add_u32_e32 v220, v0, v166
	ds_read_b128 v[220:223], v220 offset:43008
	v_add_u32_e32 v106, v0, v172
	ds_read_b128 v[106:109], v106 offset:43008
	v_add_u32_e32 v110, v0, v173
	ds_read_b128 v[110:113], v110 offset:43008
	v_add_u32_e32 v236, v0, v174
	ds_read_b128 v[236:239], v236 offset:43008
	v_subrev_u32_e32 v0, s30, v130
	v_cndmask_b32_e64 v0, v0, v217, s[38:39]
	s_waitcnt lgkmcnt(7)
	v_mfma_f32_32x32x16_bf16 v[66:81], v[66:69], v[114:117], 0
	s_waitcnt lgkmcnt(6)
	v_mfma_f32_32x32x16_bf16 v[66:81], v[98:101], v[118:121], v[66:81]
	s_waitcnt lgkmcnt(5)
	v_mfma_f32_32x32x16_bf16 v[66:81], v[102:105], v[122:125], v[66:81]
	s_waitcnt lgkmcnt(4)
	v_mfma_f32_32x32x16_bf16 v[66:81], v[178:181], v[126:129], v[66:81]
	s_waitcnt lgkmcnt(3)
	v_mfma_f32_32x32x16_bf16 v[220:235], v[220:223], v[114:117], 0
	s_waitcnt lgkmcnt(2)
	v_mfma_f32_32x32x16_bf16 v[220:235], v[106:109], v[118:121], v[220:235]
	s_waitcnt lgkmcnt(1)
	v_mfma_f32_32x32x16_bf16 v[220:235], v[110:113], v[122:125], v[220:235]
	s_waitcnt lgkmcnt(0)
	v_mfma_f32_32x32x16_bf16 v[220:235], v[236:239], v[126:129], v[220:235]
	v_add_u32_e32 v177, s53, v175
	ds_read_b128 v[110:113], v177 offset:38912
	ds_read_b128 v[106:109], v177 offset:39936
	ds_read_b128 v[102:105], v177 offset:40960
	ds_read_b128 v[98:101], v177 offset:41984
	ds_read_b128 v[236:239], v177 offset:47104
	ds_read_b128 v[240:243], v177 offset:48128
	ds_read_b128 v[244:247], v177 offset:49152
	ds_read_b128 v[248:251], v177 offset:50176
	v_add_u32_e32 v177, 0x186a0, v0
	v_subrev_u32_e32 v178, 32, v177
	v_cmp_lt_i32_e64 s[40:41], s96, v0
	v_cmp_gt_u32_e32 vcc, s9, v177
	s_cbranch_vccz .Lnsj_nomask_a
	v_cmp_le_u32_e32 vcc, v142, v177
	s_nop 1
	v_cndmask_b32_e32 v66, v212, v66, vcc
	v_cmp_le_u32_e32 vcc, v143, v177
	s_nop 1
	v_cndmask_b32_e32 v67, v212, v67, vcc
	v_cmp_le_u32_e32 vcc, v144, v177
	s_nop 1
	v_cndmask_b32_e32 v68, v212, v68, vcc
	v_cmp_le_u32_e32 vcc, v145, v177
	s_nop 1
	v_cndmask_b32_e32 v69, v212, v69, vcc
	v_cmp_le_u32_e32 vcc, v146, v177
	s_nop 1
	v_cndmask_b32_e32 v70, v212, v70, vcc
	v_cmp_le_u32_e32 vcc, v147, v177
	s_nop 1
	v_cndmask_b32_e32 v71, v212, v71, vcc
	v_cmp_le_u32_e32 vcc, v148, v177
	s_nop 1
	v_cndmask_b32_e32 v72, v212, v72, vcc
	v_cmp_le_u32_e32 vcc, v149, v177
	s_nop 1
	v_cndmask_b32_e32 v73, v212, v73, vcc
	v_cmp_le_u32_e32 vcc, v150, v177
	s_nop 1
	v_cndmask_b32_e32 v74, v212, v74, vcc
	v_cmp_le_u32_e32 vcc, v151, v177
	s_nop 1
	v_cndmask_b32_e32 v75, v212, v75, vcc
	v_cmp_le_u32_e32 vcc, v152, v177
	s_nop 1
	v_cndmask_b32_e32 v76, v212, v76, vcc
	v_cmp_le_u32_e32 vcc, v153, v177
	s_nop 1
	v_cndmask_b32_e32 v77, v212, v77, vcc
	v_cmp_le_u32_e32 vcc, v162, v177
	s_nop 1
	v_cndmask_b32_e32 v78, v212, v78, vcc
	v_cmp_le_u32_e32 vcc, v163, v177
	s_nop 1
	v_cndmask_b32_e32 v79, v212, v79, vcc
	v_cmp_le_u32_e32 vcc, v164, v177
	s_nop 1
	v_cndmask_b32_e32 v80, v212, v80, vcc
	v_cmp_le_u32_e32 vcc, v165, v177
	s_nop 1
	v_cndmask_b32_e32 v81, v212, v81, vcc
.Lnsj_nomask_a:
	v_max3_f32 v0, v66, v67, v68
	v_max3_f32 v179, v69, v70, v71
	v_max3_f32 v180, v72, v73, v74
	v_max3_f32 v0, v0, v179, v180
	v_max3_f32 v179, v75, v76, v77
	v_max3_f32 v180, v78, v79, v80
	v_max3_f32 v179, v179, v180, v81
	v_max_f32_e32 v0, v0, v179
	s_nop 3
	v_cmp_gt_u32_e32 vcc, s9, v178
	s_cbranch_vccz .Lnsj_nomask_b
	v_cmp_le_u32_e32 vcc, v142, v178
	s_nop 1
	v_cndmask_b32_e32 v220, v212, v220, vcc
	v_cmp_le_u32_e32 vcc, v143, v178
	s_nop 1
	v_cndmask_b32_e32 v221, v212, v221, vcc
	v_cmp_le_u32_e32 vcc, v144, v178
	s_nop 1
	v_cndmask_b32_e32 v222, v212, v222, vcc
	v_cmp_le_u32_e32 vcc, v145, v178
	s_nop 1
	v_cndmask_b32_e32 v223, v212, v223, vcc
	v_cmp_le_u32_e32 vcc, v146, v178
	s_nop 1
	v_cndmask_b32_e32 v224, v212, v224, vcc
	v_cmp_le_u32_e32 vcc, v147, v178
	s_nop 1
	v_cndmask_b32_e32 v225, v212, v225, vcc
	v_cmp_le_u32_e32 vcc, v148, v178
	s_nop 1
	v_cndmask_b32_e32 v226, v212, v226, vcc
	v_cmp_le_u32_e32 vcc, v149, v178
	s_nop 1
	v_cndmask_b32_e32 v227, v212, v227, vcc
	v_cmp_le_u32_e32 vcc, v150, v178
	s_nop 1
	v_cndmask_b32_e32 v228, v212, v228, vcc
	v_cmp_le_u32_e32 vcc, v151, v178
	s_nop 1
	v_cndmask_b32_e32 v229, v212, v229, vcc
	v_cmp_le_u32_e32 vcc, v152, v178
	s_nop 1
	v_cndmask_b32_e32 v230, v212, v230, vcc
	v_cmp_le_u32_e32 vcc, v153, v178
	s_nop 1
	v_cndmask_b32_e32 v231, v212, v231, vcc
	v_cmp_le_u32_e32 vcc, v162, v178
	s_nop 1
	v_cndmask_b32_e32 v232, v212, v232, vcc
	v_cmp_le_u32_e32 vcc, v163, v178
	s_nop 1
	v_cndmask_b32_e32 v233, v212, v233, vcc
	v_cmp_le_u32_e32 vcc, v164, v178
	s_nop 1
	v_cndmask_b32_e32 v234, v212, v234, vcc
	v_cmp_le_u32_e32 vcc, v165, v178
	s_nop 1
	v_cndmask_b32_e32 v235, v212, v235, vcc
.Lnsj_nomask_b:
	v_max3_f32 v179, v220, v221, v222
	v_max3_f32 v180, v223, v224, v225
	v_max3_f32 v181, v226, v227, v228
	v_max3_f32 v179, v179, v180, v181
	v_max3_f32 v180, v229, v230, v231
	v_max3_f32 v181, v232, v233, v234
	v_max3_f32 v180, v180, v181, v235
	v_max3_f32 v0, v0, v179, v180
	v_cndmask_b32_e64 v0, v212, v0, s[40:41]
	v_mov_b32_e32 v177, v0
	s_nop 1
	v_permlane32_swap_b32_e32 v0, v177
	v_max_f32_e32 v0, v0, v177
	v_add_f32_e32 v177, 0x41800000, v176
	v_cmp_gt_f32_e32 vcc, v0, v177
	s_cbranch_vccz .Lnsj_norescale
	s_nop 0
	v_cndmask_b32_e32 v177, v176, v0, vcc
	v_sub_f32_e32 v0, v176, v177
	v_exp_f32_e32 v0, v0
	v_mov_b32_e32 v176, v177
	s_nop 0
	v_mul_f32_e32 v161, v161, v0
	v_pk_mul_f32 v[64:65], v[64:65], v[0:1] op_sel_hi:[1,0]
	v_pk_mul_f32 v[62:63], v[62:63], v[0:1] op_sel_hi:[1,0]
	v_pk_mul_f32 v[60:61], v[60:61], v[0:1] op_sel_hi:[1,0]
	v_pk_mul_f32 v[58:59], v[58:59], v[0:1] op_sel_hi:[1,0]
	v_pk_mul_f32 v[56:57], v[56:57], v[0:1] op_sel_hi:[1,0]
	v_pk_mul_f32 v[54:55], v[54:55], v[0:1] op_sel_hi:[1,0]
	v_pk_mul_f32 v[52:53], v[52:53], v[0:1] op_sel_hi:[1,0]
	v_pk_mul_f32 v[50:51], v[50:51], v[0:1] op_sel_hi:[1,0]
	v_pk_mul_f32 v[48:49], v[48:49], v[0:1] op_sel_hi:[1,0]
	v_pk_mul_f32 v[46:47], v[46:47], v[0:1] op_sel_hi:[1,0]
	v_pk_mul_f32 v[44:45], v[44:45], v[0:1] op_sel_hi:[1,0]
	v_pk_mul_f32 v[42:43], v[42:43], v[0:1] op_sel_hi:[1,0]
	v_pk_mul_f32 v[40:41], v[40:41], v[0:1] op_sel_hi:[1,0]
	v_pk_mul_f32 v[38:39], v[38:39], v[0:1] op_sel_hi:[1,0]
	v_pk_mul_f32 v[36:37], v[36:37], v[0:1] op_sel_hi:[1,0]
	v_pk_mul_f32 v[34:35], v[34:35], v[0:1] op_sel_hi:[1,0]

.LBB0_913:
	s_or_b64 exec, exec, s[0:1]
	v_readlane_b32 s0, v254, 45
	v_readlane_b32 s1, v254, 46
	v_mov_b32_e32 v0, v199
	s_andn2_b64 vcc, exec, s[0:1]
	s_waitcnt lgkmcnt(0)
	s_barrier
	s_cbranch_vccnz .LBB0_943
	v_readlane_b32 s12, v255, 14
	v_readlane_b32 s40, v252, 34
	s_mul_i32 s0, s12, 0x1c0000
	v_readlane_b32 s42, v252, 36
	v_readlane_b32 s43, v252, 37
	s_add_u32 s56, s42, s0
	s_addc_u32 s57, s43, 0
	s_mul_i32 s0, s12, 0x600000
	v_readlane_b32 s41, v252, 35
	s_add_u32 s0, s40, s0
	s_addc_u32 s1, s41, 0
	s_mov_b32 s58, 0
	s_cmp_eq_u32 s73, 64
	s_cbranch_scc0 .Lp4_noremap
	s_and_b32 s98, s72, 31
	s_lshl_b32 s98, s98, 1
	s_lshr_b32 s72, s72, 5
	s_or_b32 s72, s72, s98
.Lp4_noremap:
	s_mov_b32 s30, s72
	v_readlane_b32 s13, v255, 15
	v_readlane_b32 s44, v252, 38
	v_readlane_b32 s45, v252, 39
	v_readlane_b32 s46, v252, 40
	v_readlane_b32 s47, v252, 41
	v_readlane_b32 s48, v252, 42
	v_readlane_b32 s49, v252, 43
	v_readlane_b32 s50, v252, 44
	v_readlane_b32 s51, v252, 45
	v_readlane_b32 s52, v252, 46
	v_readlane_b32 s53, v252, 47
	v_readlane_b32 s54, v252, 48
	v_readlane_b32 s55, v252, 49
	s_branch .LBB0_916

.LBB0_942:
	s_cmp_eq_u32 s73, 64
	s_cbranch_scc0 .Lp4_norest
	s_and_b32 s98, s72, 1
	s_lshl_b32 s98, s98, 5
	s_lshr_b32 s72, s72, 1
	s_or_b32 s72, s72, s98
